# baseline (speedup 1.0000x reference)
; #define MFMA32(a, b, c) __builtin_amdgcn_mfma_f32_32x32x16_bf16((a), (b), (c), 0, 0, 0)
; DI void finishSM(f32x16& p0, f32x16& p1, float alpha, float& l_reg, bf16x8& pa0, bf16x8& pa1, bf16x8& pa2, bf16x8& pa3) {
; #pragma unroll
;     for (int r = 0; r < 16; ++r) p1[r] = __builtin_amdgcn_exp2f(p1[r]);
;     float ps = 0;
; #pragma unroll
;     for (int r = 0; r < 16; ++r) ps += p0[r];
; #pragma unroll
;     for (int r = 0; r < 16; ++r) ps += p1[r];
;     { auto rr = __builtin_amdgcn_permlane32_swap(__float_as_uint(ps), __float_as_uint(ps), false, false);
;       ps = __uint_as_float(rr[0]) + __uint_as_float(rr[1]); }
;     l_reg = l_reg * alpha + ps;
;     ...
;     PK4(p0, 0, pa0); PK4(p0, 8, pa1); PK4(p1, 0, pa2); PK4(p1, 8, pa3);
;     ...
; }
; template <int KB>
; DI void qkt(f32x16& p0, f32x16& p1, const char* K_lds, int r32, int hi, const bf16x8* qr, const float* bb) {
; #pragma unroll
;     for (int g = 0; g < 4; ++g) {
;         const f32x4 b0 = *(const f32x4*)(bb + KB * 64 + 8 * g), b1 = *(const f32x4*)(bb + KB * 64 + 32 + 8 * g);
; #pragma unroll
;         for (int j = 0; j < 4; ++j) { p0[4 * g + j] = b0[j]; p1[4 * g + j] = b1[j]; }
;     }
;     const char* kb[4];
; #pragma unroll
;     for (int dd = 0; dd < 4; ++dd) kb[dd] = K_lds + KB * SHM_K + KSWZ(r32, (dd * 16 + hi * 8) * 2);
; #pragma unroll
;     for (int d0 = 0; d0 < 8; ++d0) { const char* a = kb[d0 & 3] + (d0 >> 2) * 128;
;         bf16x8 b0 = *reinterpret_cast<const bf16x8*>(a);
;         bf16x8 b1 = *reinterpret_cast<const bf16x8*>(a + 32 * 256);
;         p0 = MFMA32(b0, qr[d0], p0);
;         p1 = MFMA32(b1, qr[d0], p1); }
; }
.Lfa_c2_skip:
	ds_read_b128 v[114:117], v235
	ds_read_b128 v[118:121], v235 offset:32
	ds_read_b128 v[98:101], v235 offset:128
	ds_read_b128 v[102:105], v235 offset:160
	ds_read_b128 v[122:125], v235 offset:64
	ds_read_b128 v[106:109], v235 offset:192
	ds_read_b128 v[126:129], v235 offset:96
	ds_read_b128 v[110:113], v235 offset:224
	ds_read_b128 v[82:85], v233 offset:32768
	ds_read_b128 v[182:185], v233 offset:40960
	v_exp_f32_e32 v87, v87
	v_exp_f32_e32 v88, v88
	v_exp_f32_e32 v89, v89
	s_waitcnt lgkmcnt(1)
	v_mfma_f32_32x32x16_bf16 v[114:129], v[82:85], v[158:161], v[114:129]
	v_exp_f32_e32 v90, v90
	v_exp_f32_e32 v91, v91
	v_exp_f32_e32 v92, v92
	v_exp_f32_e32 v93, v93
	v_exp_f32_e32 v94, v94
	s_waitcnt lgkmcnt(0)
	v_mfma_f32_32x32x16_bf16 v[98:113], v[182:185], v[158:161], v[98:113]
	ds_read_b128 v[82:85], v234 offset:32768
	ds_read_b128 v[182:185], v234 offset:40960
	s_waitcnt lgkmcnt(1)
	v_mfma_f32_32x32x16_bf16 v[114:129], v[82:85], v[154:157], v[114:129]
	v_add_f32_e32 v200, 0, v66
	v_add_f32_e32 v200, v67, v200
	s_waitcnt lgkmcnt(0)
	v_mfma_f32_32x32x16_bf16 v[98:113], v[182:185], v[154:157], v[98:113]
	v_add_f32_e32 v200, v68, v200
	v_add_f32_e32 v200, v69, v200
	ds_read_b128 v[82:85], v232 offset:32768
	ds_read_b128 v[182:185], v232 offset:40960
	s_waitcnt lgkmcnt(1)
	v_mfma_f32_32x32x16_bf16 v[114:129], v[82:85], v[150:153], v[114:129]
	v_add_f32_e32 v200, v70, v200
	v_add_f32_e32 v200, v71, v200
	s_waitcnt lgkmcnt(0)
	v_mfma_f32_32x32x16_bf16 v[98:113], v[182:185], v[150:153], v[98:113]
	v_add_f32_e32 v200, v72, v200
	v_add_f32_e32 v200, v73, v200
	ds_read_b128 v[82:85], v231 offset:32768
	ds_read_b128 v[182:185], v231 offset:40960
	s_waitcnt lgkmcnt(1)
	v_mfma_f32_32x32x16_bf16 v[114:129], v[82:85], v[146:149], v[114:129]
	v_add_f32_e32 v200, v74, v200
	v_add_f32_e32 v200, v75, v200
	s_waitcnt lgkmcnt(0)
	v_mfma_f32_32x32x16_bf16 v[98:113], v[182:185], v[146:149], v[98:113]
	v_add_f32_e32 v200, v76, v200
	v_add_f32_e32 v200, v77, v200
	ds_read_b128 v[82:85], v233 offset:32896
	ds_read_b128 v[182:185], v233 offset:41088
	s_waitcnt lgkmcnt(1)
	v_mfma_f32_32x32x16_bf16 v[114:129], v[82:85], v[142:145], v[114:129]
	v_add_f32_e32 v200, v78, v200
	v_add_f32_e32 v200, v79, v200
	s_waitcnt lgkmcnt(0)
	v_mfma_f32_32x32x16_bf16 v[98:113], v[182:185], v[142:145], v[98:113]
	v_add_f32_e32 v200, v80, v200
	v_add_f32_e32 v200, v81, v200
	ds_read_b128 v[82:85], v234 offset:32896
	ds_read_b128 v[182:185], v234 offset:41088
	s_waitcnt lgkmcnt(1)
	v_mfma_f32_32x32x16_bf16 v[114:129], v[82:85], v[138:141], v[114:129]
	v_exp_f32_e32 v201, v97
	v_exp_f32_e32 v97, v178
	s_waitcnt lgkmcnt(0)
	v_mfma_f32_32x32x16_bf16 v[98:113], v[182:185], v[138:141], v[98:113]
	v_exp_f32_e32 v202, v86
	v_exp_f32_e32 v86, v179
	ds_read_b128 v[82:85], v232 offset:32896
	ds_read_b128 v[182:185], v232 offset:41088
	s_waitcnt lgkmcnt(1)
	v_mfma_f32_32x32x16_bf16 v[114:129], v[82:85], v[134:137], v[114:129]
	v_exp_f32_e32 v203, v95
	v_exp_f32_e32 v95, v180
	s_waitcnt lgkmcnt(0)
	v_mfma_f32_32x32x16_bf16 v[98:113], v[182:185], v[134:137], v[98:113]
	v_exp_f32_e32 v216, v96
	v_exp_f32_e32 v96, v181
	ds_read_b128 v[82:85], v231 offset:32896
	ds_read_b128 v[182:185], v231 offset:41088
	s_waitcnt lgkmcnt(1)
	v_mfma_f32_32x32x16_bf16 v[114:129], v[82:85], v[130:133], v[114:129]
	v_add_f32_e32 v178, v202, v200
	v_add_f32_e32 v178, v203, v178
	v_add_f32_e32 v178, v216, v178
	v_add_f32_e32 v178, v201, v178
	v_add_f32_e32 v178, v86, v178
	v_add_f32_e32 v178, v87, v178
	v_add_f32_e32 v178, v88, v178
	v_add_f32_e32 v178, v89, v178
	v_add_f32_e32 v178, v90, v178
	v_add_f32_e32 v178, v91, v178
	v_mov_b32_e32 v85, v201
	v_mov_b32_e32 v82, v202
	v_mov_b32_e32 v83, v203
	v_mov_b32_e32 v84, v216
	s_waitcnt lgkmcnt(0)
	v_mfma_f32_32x32x16_bf16 v[98:113], v[182:185], v[130:133], v[98:113]
	v_add_f32_e32 v178, v92, v178
	v_add_f32_e32 v178, v93, v178
	v_add_f32_e32 v178, v94, v178
	v_add_f32_e32 v178, v95, v178
	v_add_f32_e32 v178, v96, v178
	v_add_f32_e32 v246, v97, v178
	v_mov_b32_e32 v247, v246
	v_cvt_pk_bf16_f32 v178, v66, v67
	v_cvt_pk_bf16_f32 v179, v68, v69
	v_cvt_pk_bf16_f32 v180, v70, v71
	v_cvt_pk_bf16_f32 v181, v72, v73
	v_cvt_pk_bf16_f32 v182, v74, v75
	v_cvt_pk_bf16_f32 v183, v76, v77
	v_cvt_pk_bf16_f32 v184, v78, v79
	v_cvt_pk_bf16_f32 v185, v80, v81
	v_cvt_pk_bf16_f32 v186, v82, v83
	v_cvt_pk_bf16_f32 v187, v84, v85
	v_cvt_pk_bf16_f32 v188, v86, v87
	v_cvt_pk_bf16_f32 v189, v88, v89
	v_cvt_pk_bf16_f32 v190, v90, v91
	v_cvt_pk_bf16_f32 v191, v92, v93
	v_cvt_pk_bf16_f32 v192, v94, v95
	v_cvt_pk_bf16_f32 v193, v96, v97
	s_nop 1
	v_permlane32_swap_b32_e32 v246, v247
	v_permlane32_swap_b32_e32 v178, v180
	v_permlane32_swap_b32_e32 v179, v181
	v_permlane32_swap_b32_e32 v182, v184
	v_permlane32_swap_b32_e32 v183, v185
	v_permlane32_swap_b32_e32 v186, v188
	v_permlane32_swap_b32_e32 v187, v189
	v_permlane32_swap_b32_e32 v190, v192
	v_permlane32_swap_b32_e32 v191, v193
